# G3 epilogue (both stages) hand-pipelined: x loads double-buffered with counted vmcnt, stage-2 loads up front; same arithmetic per element
# baseline (speedup 1.0000x reference)
.LBB0_547:
	s_ashr_i32 s33, s48, 31
	s_lshr_b32 s33, s33, 27
	s_add_i32 s33, s48, s33
	v_lshl_add_u32 v158, s48, 8, v196
	v_lshl_or_b32 v156, s52, 8, v198
	s_ashr_i32 s43, s33, 5
	v_ashrrev_i32_e32 v159, 31, v158
	s_mul_hi_i32 s41, s43, 0x6000
	s_mulk_i32 s43, 0x6000
	v_ashrrev_i32_e32 v157, 31, v156
	v_lshlrev_b64 v[102:103], 10, v[158:159]
	s_add_u32 s52, s72, s43
	v_lshl_add_u64 v[102:103], v[102:103], 0, v[156:157]
	s_addc_u32 s53, s73, s41
	v_lshl_add_u64 v[192:193], v[102:103], 2, s[16:17]
	v_lshl_add_u64 v[100:101], v[156:157], 2, s[52:53]
	v_lshl_add_u64 v[194:195], v[102:103], 1, s[30:31]
	v_lshl_add_u64 v[204:205], v[158:159], 2, s[20:21]
	s_mov_b32 s99, 0
	s_mov_b32 s101, 0
	global_load_dwordx4 v[160:163], v[192:193], off offset:0
	global_load_dwordx4 v[164:167], v[192:193], off offset:64
	global_load_dwordx4 v[168:171], v[192:193], off offset:512
	global_load_dwordx4 v[172:175], v[192:193], off offset:576
	s_mov_b32 s98, 0x10000
	v_lshl_add_u64 v[206:207], v[192:193], 0, s[98:99]
	global_load_dwordx4 v[116:119], v[100:101], off
	global_load_dwordx4 v[112:115], v[100:101], off offset:64
	global_load_dwordx4 v[108:111], v[100:101], off offset:512
	s_nop 0
	global_load_dwordx4 v[100:103], v[100:101], off offset:576
	global_load_dwordx4 v[176:179], v[206:207], off offset:0
	global_load_dwordx4 v[180:183], v[206:207], off offset:64
	global_load_dwordx4 v[184:187], v[206:207], off offset:512
	global_load_dwordx4 v[188:191], v[206:207], off offset:576
	s_waitcnt vmcnt(4)
	v_pk_fma_f32 v[140:141], v[140:141], v[116:117], v[160:161]
	v_pk_fma_f32 v[142:143], v[142:143], v[118:119], v[162:163]
	v_pk_fma_f32 v[136:137], v[136:137], v[112:113], v[164:165]
	v_pk_fma_f32 v[138:139], v[138:139], v[114:115], v[166:167]
	v_pk_fma_f32 v[132:133], v[132:133], v[108:109], v[168:169]
	v_pk_fma_f32 v[134:135], v[134:135], v[110:111], v[170:171]
	v_pk_fma_f32 v[128:129], v[128:129], v[100:101], v[172:173]
	v_pk_fma_f32 v[130:131], v[130:131], v[102:103], v[174:175]
	s_mov_b32 s98, 0x20000
	v_lshl_add_u64 v[206:207], v[192:193], 0, s[98:99]
	global_load_dwordx4 v[160:163], v[206:207], off offset:0
	global_load_dwordx4 v[164:167], v[206:207], off offset:64
	global_load_dwordx4 v[168:171], v[206:207], off offset:512
	global_load_dwordx4 v[172:175], v[206:207], off offset:576
	v_mul_f32_e32 v214, v140, v140
	v_mul_f32_e32 v215, v141, v141
	v_fmac_f32_e32 v214, v142, v142
	v_fmac_f32_e32 v215, v143, v143
	v_fmac_f32_e32 v214, v136, v136
	v_fmac_f32_e32 v215, v137, v137
	v_fmac_f32_e32 v214, v138, v138
	v_fmac_f32_e32 v215, v139, v139
	v_fmac_f32_e32 v214, v132, v132
	v_fmac_f32_e32 v215, v133, v133
	v_fmac_f32_e32 v214, v134, v134
	v_fmac_f32_e32 v215, v135, v135
	v_fmac_f32_e32 v214, v128, v128
	v_fmac_f32_e32 v215, v129, v129
	v_fmac_f32_e32 v214, v130, v130
	v_fmac_f32_e32 v215, v131, v131
	v_add_f32_e32 v214, v214, v215
	ds_bpermute_b32 v216, v210, v214
	v_cvt_pk_f16_f32 v218, v140, v141
	v_cvt_pk_f16_f32 v219, v142, v143
	global_store_dwordx2 v[194:195], v[218:219], off offset:0
	v_cvt_pk_f16_f32 v220, v136, v137
	v_cvt_pk_f16_f32 v221, v138, v139
	global_store_dwordx2 v[194:195], v[220:221], off offset:32
	v_cvt_pk_f16_f32 v222, v132, v133
	v_cvt_pk_f16_f32 v223, v134, v135
	global_store_dwordx2 v[194:195], v[222:223], off offset:256
	v_cvt_pk_f16_f32 v224, v128, v129
	v_cvt_pk_f16_f32 v225, v130, v131
	global_store_dwordx2 v[194:195], v[224:225], off offset:288
	s_waitcnt lgkmcnt(0)
	v_add_f32_e32 v214, v214, v216
	ds_bpermute_b32 v216, v211, v214
	s_and_saveexec_b64 s[52:53], s[4:5]
	s_waitcnt lgkmcnt(0)
	v_add_f32_e32 v214, v214, v216
	global_atomic_add_f32 v[204:205], v214, off offset:0
	s_or_b64 exec, exec, s[52:53]
	s_waitcnt vmcnt(9)
	v_pk_fma_f32 v[124:125], v[124:125], v[116:117], v[176:177]
	v_pk_fma_f32 v[126:127], v[126:127], v[118:119], v[178:179]
	v_pk_fma_f32 v[120:121], v[120:121], v[112:113], v[180:181]
	v_pk_fma_f32 v[122:123], v[122:123], v[114:115], v[182:183]
	v_pk_fma_f32 v[104:105], v[104:105], v[108:109], v[184:185]
	v_pk_fma_f32 v[106:107], v[106:107], v[110:111], v[186:187]
	v_pk_fma_f32 v[96:97], v[96:97], v[100:101], v[188:189]
	v_pk_fma_f32 v[98:99], v[98:99], v[102:103], v[190:191]
	s_mov_b32 s98, 0x30000
	v_lshl_add_u64 v[206:207], v[192:193], 0, s[98:99]
	global_load_dwordx4 v[176:179], v[206:207], off offset:0
	global_load_dwordx4 v[180:183], v[206:207], off offset:64
	global_load_dwordx4 v[184:187], v[206:207], off offset:512
	global_load_dwordx4 v[188:191], v[206:207], off offset:576
	v_mul_f32_e32 v214, v124, v124
	v_mul_f32_e32 v215, v125, v125
	v_fmac_f32_e32 v214, v126, v126
	v_fmac_f32_e32 v215, v127, v127
	v_fmac_f32_e32 v214, v120, v120
	v_fmac_f32_e32 v215, v121, v121
	v_fmac_f32_e32 v214, v122, v122
	v_fmac_f32_e32 v215, v123, v123
	v_fmac_f32_e32 v214, v104, v104
	v_fmac_f32_e32 v215, v105, v105
	v_fmac_f32_e32 v214, v106, v106
	v_fmac_f32_e32 v215, v107, v107
	v_fmac_f32_e32 v214, v96, v96
	v_fmac_f32_e32 v215, v97, v97
	v_fmac_f32_e32 v214, v98, v98
	v_fmac_f32_e32 v215, v99, v99
	v_add_f32_e32 v214, v214, v215
	ds_bpermute_b32 v216, v210, v214
	s_mov_b32 s100, 0x8000
	v_lshl_add_u64 v[212:213], v[194:195], 0, s[100:101]
	v_cvt_pk_f16_f32 v218, v124, v125
	v_cvt_pk_f16_f32 v219, v126, v127
	global_store_dwordx2 v[212:213], v[218:219], off offset:0
	v_cvt_pk_f16_f32 v220, v120, v121
	v_cvt_pk_f16_f32 v221, v122, v123
	global_store_dwordx2 v[212:213], v[220:221], off offset:32
	v_cvt_pk_f16_f32 v222, v104, v105
	v_cvt_pk_f16_f32 v223, v106, v107
	global_store_dwordx2 v[212:213], v[222:223], off offset:256
	v_cvt_pk_f16_f32 v224, v96, v97
	v_cvt_pk_f16_f32 v225, v98, v99
	global_store_dwordx2 v[212:213], v[224:225], off offset:288
	s_waitcnt lgkmcnt(0)
	v_add_f32_e32 v214, v214, v216
	ds_bpermute_b32 v216, v211, v214
	s_and_saveexec_b64 s[52:53], s[4:5]
	s_waitcnt lgkmcnt(0)
	v_add_f32_e32 v214, v214, v216
	global_atomic_add_f32 v[204:205], v214, off offset:64
	s_or_b64 exec, exec, s[52:53]
	s_waitcnt vmcnt(14)
	v_pk_fma_f32 v[92:93], v[92:93], v[116:117], v[160:161]
	v_pk_fma_f32 v[94:95], v[94:95], v[118:119], v[162:163]
	v_pk_fma_f32 v[88:89], v[88:89], v[112:113], v[164:165]
	v_pk_fma_f32 v[90:91], v[90:91], v[114:115], v[166:167]
	v_pk_fma_f32 v[84:85], v[84:85], v[108:109], v[168:169]
	v_pk_fma_f32 v[86:87], v[86:87], v[110:111], v[170:171]
	v_pk_fma_f32 v[80:81], v[80:81], v[100:101], v[172:173]
	v_pk_fma_f32 v[82:83], v[82:83], v[102:103], v[174:175]
	s_mov_b32 s98, 0x80000
	v_lshl_add_u64 v[206:207], v[192:193], 0, s[98:99]
	global_load_dwordx4 v[160:163], v[206:207], off offset:0
	global_load_dwordx4 v[164:167], v[206:207], off offset:64
	global_load_dwordx4 v[168:171], v[206:207], off offset:512
	global_load_dwordx4 v[172:175], v[206:207], off offset:576
	v_mul_f32_e32 v214, v92, v92
	v_mul_f32_e32 v215, v93, v93
	v_fmac_f32_e32 v214, v94, v94
	v_fmac_f32_e32 v215, v95, v95
	v_fmac_f32_e32 v214, v88, v88
	v_fmac_f32_e32 v215, v89, v89
	v_fmac_f32_e32 v214, v90, v90
	v_fmac_f32_e32 v215, v91, v91
	v_fmac_f32_e32 v214, v84, v84
	v_fmac_f32_e32 v215, v85, v85
	v_fmac_f32_e32 v214, v86, v86
	v_fmac_f32_e32 v215, v87, v87
	v_fmac_f32_e32 v214, v80, v80
	v_fmac_f32_e32 v215, v81, v81
	v_fmac_f32_e32 v214, v82, v82
	v_fmac_f32_e32 v215, v83, v83
	v_add_f32_e32 v214, v214, v215
	ds_bpermute_b32 v216, v210, v214
	s_mov_b32 s100, 0x10000
	v_lshl_add_u64 v[212:213], v[194:195], 0, s[100:101]
	v_cvt_pk_f16_f32 v218, v92, v93
	v_cvt_pk_f16_f32 v219, v94, v95
	global_store_dwordx2 v[212:213], v[218:219], off offset:0
	v_cvt_pk_f16_f32 v220, v88, v89
	v_cvt_pk_f16_f32 v221, v90, v91
	global_store_dwordx2 v[212:213], v[220:221], off offset:32
	v_cvt_pk_f16_f32 v222, v84, v85
	v_cvt_pk_f16_f32 v223, v86, v87
	global_store_dwordx2 v[212:213], v[222:223], off offset:256
	v_cvt_pk_f16_f32 v224, v80, v81
	v_cvt_pk_f16_f32 v225, v82, v83
	global_store_dwordx2 v[212:213], v[224:225], off offset:288
	s_waitcnt lgkmcnt(0)
	v_add_f32_e32 v214, v214, v216
	ds_bpermute_b32 v216, v211, v214
	s_and_saveexec_b64 s[52:53], s[4:5]
	s_waitcnt lgkmcnt(0)
	v_add_f32_e32 v214, v214, v216
	global_atomic_add_f32 v[204:205], v214, off offset:128
	s_or_b64 exec, exec, s[52:53]
	s_waitcnt vmcnt(14)
	v_pk_fma_f32 v[76:77], v[76:77], v[116:117], v[176:177]
	v_pk_fma_f32 v[78:79], v[78:79], v[118:119], v[178:179]
	v_pk_fma_f32 v[72:73], v[72:73], v[112:113], v[180:181]
	v_pk_fma_f32 v[74:75], v[74:75], v[114:115], v[182:183]
	v_pk_fma_f32 v[68:69], v[68:69], v[108:109], v[184:185]
	v_pk_fma_f32 v[70:71], v[70:71], v[110:111], v[186:187]
	v_pk_fma_f32 v[64:65], v[64:65], v[100:101], v[188:189]
	v_pk_fma_f32 v[66:67], v[66:67], v[102:103], v[190:191]
	s_mov_b32 s98, 0x90000
	v_lshl_add_u64 v[206:207], v[192:193], 0, s[98:99]
	global_load_dwordx4 v[176:179], v[206:207], off offset:0
	global_load_dwordx4 v[180:183], v[206:207], off offset:64
	global_load_dwordx4 v[184:187], v[206:207], off offset:512
	global_load_dwordx4 v[188:191], v[206:207], off offset:576
	v_mul_f32_e32 v214, v76, v76
	v_mul_f32_e32 v215, v77, v77
	v_fmac_f32_e32 v214, v78, v78
	v_fmac_f32_e32 v215, v79, v79
	v_fmac_f32_e32 v214, v72, v72
	v_fmac_f32_e32 v215, v73, v73
	v_fmac_f32_e32 v214, v74, v74
	v_fmac_f32_e32 v215, v75, v75
	v_fmac_f32_e32 v214, v68, v68
	v_fmac_f32_e32 v215, v69, v69
	v_fmac_f32_e32 v214, v70, v70
	v_fmac_f32_e32 v215, v71, v71
	v_fmac_f32_e32 v214, v64, v64
	v_fmac_f32_e32 v215, v65, v65
	v_fmac_f32_e32 v214, v66, v66
	v_fmac_f32_e32 v215, v67, v67
	v_add_f32_e32 v214, v214, v215
	ds_bpermute_b32 v216, v210, v214
	s_mov_b32 s100, 0x18000
	v_lshl_add_u64 v[212:213], v[194:195], 0, s[100:101]
	v_cvt_pk_f16_f32 v218, v76, v77
	v_cvt_pk_f16_f32 v219, v78, v79
	global_store_dwordx2 v[212:213], v[218:219], off offset:0
	v_cvt_pk_f16_f32 v220, v72, v73
	v_cvt_pk_f16_f32 v221, v74, v75
	global_store_dwordx2 v[212:213], v[220:221], off offset:32
	v_cvt_pk_f16_f32 v222, v68, v69
	v_cvt_pk_f16_f32 v223, v70, v71
	global_store_dwordx2 v[212:213], v[222:223], off offset:256
	v_cvt_pk_f16_f32 v224, v64, v65
	v_cvt_pk_f16_f32 v225, v66, v67
	global_store_dwordx2 v[212:213], v[224:225], off offset:288
	s_waitcnt lgkmcnt(0)
	v_add_f32_e32 v214, v214, v216
	ds_bpermute_b32 v216, v211, v214
	s_and_saveexec_b64 s[52:53], s[4:5]
	s_waitcnt lgkmcnt(0)
	v_add_f32_e32 v214, v214, v216
	global_atomic_add_f32 v[204:205], v214, off offset:192
	s_or_b64 exec, exec, s[52:53]
	s_waitcnt vmcnt(14)
	v_pk_fma_f32 v[60:61], v[60:61], v[116:117], v[160:161]
	v_pk_fma_f32 v[62:63], v[62:63], v[118:119], v[162:163]
	v_pk_fma_f32 v[56:57], v[56:57], v[112:113], v[164:165]
	v_pk_fma_f32 v[58:59], v[58:59], v[114:115], v[166:167]
	v_pk_fma_f32 v[52:53], v[52:53], v[108:109], v[168:169]
	v_pk_fma_f32 v[54:55], v[54:55], v[110:111], v[170:171]
	v_pk_fma_f32 v[48:49], v[48:49], v[100:101], v[172:173]
	v_pk_fma_f32 v[50:51], v[50:51], v[102:103], v[174:175]
	s_mov_b32 s98, 0xa0000
	v_lshl_add_u64 v[206:207], v[192:193], 0, s[98:99]
	global_load_dwordx4 v[160:163], v[206:207], off offset:0
	global_load_dwordx4 v[164:167], v[206:207], off offset:64
	global_load_dwordx4 v[168:171], v[206:207], off offset:512
	global_load_dwordx4 v[172:175], v[206:207], off offset:576
	v_mul_f32_e32 v214, v60, v60
	v_mul_f32_e32 v215, v61, v61
	v_fmac_f32_e32 v214, v62, v62
	v_fmac_f32_e32 v215, v63, v63
	v_fmac_f32_e32 v214, v56, v56
	v_fmac_f32_e32 v215, v57, v57
	v_fmac_f32_e32 v214, v58, v58
	v_fmac_f32_e32 v215, v59, v59
	v_fmac_f32_e32 v214, v52, v52
	v_fmac_f32_e32 v215, v53, v53
	v_fmac_f32_e32 v214, v54, v54
	v_fmac_f32_e32 v215, v55, v55
	v_fmac_f32_e32 v214, v48, v48
	v_fmac_f32_e32 v215, v49, v49
	v_fmac_f32_e32 v214, v50, v50
	v_fmac_f32_e32 v215, v51, v51
	v_add_f32_e32 v214, v214, v215
	ds_bpermute_b32 v216, v210, v214
	s_mov_b32 s100, 0x40000
	v_lshl_add_u64 v[212:213], v[194:195], 0, s[100:101]
	v_cvt_pk_f16_f32 v218, v60, v61
	v_cvt_pk_f16_f32 v219, v62, v63
	global_store_dwordx2 v[212:213], v[218:219], off offset:0
	v_cvt_pk_f16_f32 v220, v56, v57
	v_cvt_pk_f16_f32 v221, v58, v59
	global_store_dwordx2 v[212:213], v[220:221], off offset:32
	v_cvt_pk_f16_f32 v222, v52, v53
	v_cvt_pk_f16_f32 v223, v54, v55
	global_store_dwordx2 v[212:213], v[222:223], off offset:256
	v_cvt_pk_f16_f32 v224, v48, v49
	v_cvt_pk_f16_f32 v225, v50, v51
	global_store_dwordx2 v[212:213], v[224:225], off offset:288
	s_waitcnt lgkmcnt(0)
	v_add_f32_e32 v214, v214, v216
	ds_bpermute_b32 v216, v211, v214
	s_and_saveexec_b64 s[52:53], s[4:5]
	s_waitcnt lgkmcnt(0)
	v_add_f32_e32 v214, v214, v216
	global_atomic_add_f32 v[204:205], v214, off offset:512
	s_or_b64 exec, exec, s[52:53]
	s_waitcnt vmcnt(14)
	v_pk_fma_f32 v[44:45], v[44:45], v[116:117], v[176:177]
	v_pk_fma_f32 v[46:47], v[46:47], v[118:119], v[178:179]
	v_pk_fma_f32 v[40:41], v[40:41], v[112:113], v[180:181]
	v_pk_fma_f32 v[42:43], v[42:43], v[114:115], v[182:183]
	v_pk_fma_f32 v[36:37], v[36:37], v[108:109], v[184:185]
	v_pk_fma_f32 v[38:39], v[38:39], v[110:111], v[186:187]
	v_pk_fma_f32 v[32:33], v[32:33], v[100:101], v[188:189]
	v_pk_fma_f32 v[34:35], v[34:35], v[102:103], v[190:191]
	s_mov_b32 s98, 0xb0000
	v_lshl_add_u64 v[206:207], v[192:193], 0, s[98:99]
	global_load_dwordx4 v[176:179], v[206:207], off offset:0
	global_load_dwordx4 v[180:183], v[206:207], off offset:64
	global_load_dwordx4 v[184:187], v[206:207], off offset:512
	global_load_dwordx4 v[188:191], v[206:207], off offset:576
	v_mul_f32_e32 v214, v44, v44
	v_mul_f32_e32 v215, v45, v45
	v_fmac_f32_e32 v214, v46, v46
	v_fmac_f32_e32 v215, v47, v47
	v_fmac_f32_e32 v214, v40, v40
	v_fmac_f32_e32 v215, v41, v41
	v_fmac_f32_e32 v214, v42, v42
	v_fmac_f32_e32 v215, v43, v43
	v_fmac_f32_e32 v214, v36, v36
	v_fmac_f32_e32 v215, v37, v37
	v_fmac_f32_e32 v214, v38, v38
	v_fmac_f32_e32 v215, v39, v39
	v_fmac_f32_e32 v214, v32, v32
	v_fmac_f32_e32 v215, v33, v33
	v_fmac_f32_e32 v214, v34, v34
	v_fmac_f32_e32 v215, v35, v35
	v_add_f32_e32 v214, v214, v215
	ds_bpermute_b32 v216, v210, v214
	s_mov_b32 s100, 0x48000
	v_lshl_add_u64 v[212:213], v[194:195], 0, s[100:101]
	v_cvt_pk_f16_f32 v218, v44, v45
	v_cvt_pk_f16_f32 v219, v46, v47
	global_store_dwordx2 v[212:213], v[218:219], off offset:0
	v_cvt_pk_f16_f32 v220, v40, v41
	v_cvt_pk_f16_f32 v221, v42, v43
	global_store_dwordx2 v[212:213], v[220:221], off offset:32
	v_cvt_pk_f16_f32 v222, v36, v37
	v_cvt_pk_f16_f32 v223, v38, v39
	global_store_dwordx2 v[212:213], v[222:223], off offset:256
	v_cvt_pk_f16_f32 v224, v32, v33
	v_cvt_pk_f16_f32 v225, v34, v35
	global_store_dwordx2 v[212:213], v[224:225], off offset:288
	s_waitcnt lgkmcnt(0)
	v_add_f32_e32 v214, v214, v216
	ds_bpermute_b32 v216, v211, v214
	s_and_saveexec_b64 s[52:53], s[4:5]
	s_waitcnt lgkmcnt(0)
	v_add_f32_e32 v214, v214, v216
	global_atomic_add_f32 v[204:205], v214, off offset:576
	s_or_b64 exec, exec, s[52:53]
	s_waitcnt vmcnt(14)
	v_pk_fma_f32 v[28:29], v[28:29], v[116:117], v[160:161]
	v_pk_fma_f32 v[30:31], v[30:31], v[118:119], v[162:163]
	v_pk_fma_f32 v[24:25], v[24:25], v[112:113], v[164:165]
	v_pk_fma_f32 v[26:27], v[26:27], v[114:115], v[166:167]
	v_pk_fma_f32 v[20:21], v[20:21], v[108:109], v[168:169]
	v_pk_fma_f32 v[22:23], v[22:23], v[110:111], v[170:171]
	v_pk_fma_f32 v[16:17], v[16:17], v[100:101], v[172:173]
	v_pk_fma_f32 v[18:19], v[18:19], v[102:103], v[174:175]
	v_mul_f32_e32 v214, v28, v28
	v_mul_f32_e32 v215, v29, v29
	v_fmac_f32_e32 v214, v30, v30
	v_fmac_f32_e32 v215, v31, v31
	v_fmac_f32_e32 v214, v24, v24
	v_fmac_f32_e32 v215, v25, v25
	v_fmac_f32_e32 v214, v26, v26
	v_fmac_f32_e32 v215, v27, v27
	v_fmac_f32_e32 v214, v20, v20
	v_fmac_f32_e32 v215, v21, v21
	v_fmac_f32_e32 v214, v22, v22
	v_fmac_f32_e32 v215, v23, v23
	v_fmac_f32_e32 v214, v16, v16
	v_fmac_f32_e32 v215, v17, v17
	v_fmac_f32_e32 v214, v18, v18
	v_fmac_f32_e32 v215, v19, v19
	v_add_f32_e32 v214, v214, v215
	ds_bpermute_b32 v216, v210, v214
	s_mov_b32 s100, 0x50000
	v_lshl_add_u64 v[212:213], v[194:195], 0, s[100:101]
	v_cvt_pk_f16_f32 v218, v28, v29
	v_cvt_pk_f16_f32 v219, v30, v31
	global_store_dwordx2 v[212:213], v[218:219], off offset:0
	v_cvt_pk_f16_f32 v220, v24, v25
	v_cvt_pk_f16_f32 v221, v26, v27
	global_store_dwordx2 v[212:213], v[220:221], off offset:32
	v_cvt_pk_f16_f32 v222, v20, v21
	v_cvt_pk_f16_f32 v223, v22, v23
	global_store_dwordx2 v[212:213], v[222:223], off offset:256
	v_cvt_pk_f16_f32 v224, v16, v17
	v_cvt_pk_f16_f32 v225, v18, v19
	global_store_dwordx2 v[212:213], v[224:225], off offset:288
	s_waitcnt lgkmcnt(0)
	v_add_f32_e32 v214, v214, v216
	ds_bpermute_b32 v216, v211, v214
	s_and_saveexec_b64 s[52:53], s[4:5]
	s_waitcnt lgkmcnt(0)
	v_add_f32_e32 v214, v214, v216
	global_atomic_add_f32 v[204:205], v214, off offset:640
	s_or_b64 exec, exec, s[52:53]
	s_waitcnt vmcnt(10)
	v_pk_fma_f32 v[12:13], v[12:13], v[116:117], v[176:177]
	v_pk_fma_f32 v[14:15], v[14:15], v[118:119], v[178:179]
	v_pk_fma_f32 v[8:9], v[8:9], v[112:113], v[180:181]
	v_pk_fma_f32 v[10:11], v[10:11], v[114:115], v[182:183]
	v_pk_fma_f32 v[4:5], v[4:5], v[108:109], v[184:185]
	v_pk_fma_f32 v[6:7], v[6:7], v[110:111], v[186:187]
	v_pk_fma_f32 v[188:189], v[0:1], v[100:101], v[188:189]
	v_pk_fma_f32 v[190:191], v[2:3], v[102:103], v[190:191]
	v_mul_f32_e32 v214, v12, v12
	v_mul_f32_e32 v215, v13, v13
	v_fmac_f32_e32 v214, v14, v14
	v_fmac_f32_e32 v215, v15, v15
	v_fmac_f32_e32 v214, v8, v8
	v_fmac_f32_e32 v215, v9, v9
	v_fmac_f32_e32 v214, v10, v10
	v_fmac_f32_e32 v215, v11, v11
	v_fmac_f32_e32 v214, v4, v4
	v_fmac_f32_e32 v215, v5, v5
	v_fmac_f32_e32 v214, v6, v6
	v_fmac_f32_e32 v215, v7, v7
	v_fmac_f32_e32 v214, v188, v188
	v_fmac_f32_e32 v215, v189, v189
	v_fmac_f32_e32 v214, v190, v190
	v_fmac_f32_e32 v215, v191, v191
	v_add_f32_e32 v214, v214, v215
	ds_bpermute_b32 v216, v210, v214
	s_mov_b32 s100, 0x58000
	v_lshl_add_u64 v[212:213], v[194:195], 0, s[100:101]
	v_cvt_pk_f16_f32 v218, v12, v13
	v_cvt_pk_f16_f32 v219, v14, v15
	global_store_dwordx2 v[212:213], v[218:219], off offset:0
	v_cvt_pk_f16_f32 v220, v8, v9
	v_cvt_pk_f16_f32 v221, v10, v11
	global_store_dwordx2 v[212:213], v[220:221], off offset:32
	v_cvt_pk_f16_f32 v222, v4, v5
	v_cvt_pk_f16_f32 v223, v6, v7
	global_store_dwordx2 v[212:213], v[222:223], off offset:256
	v_cvt_pk_f16_f32 v224, v188, v189
	v_cvt_pk_f16_f32 v225, v190, v191
	global_store_dwordx2 v[212:213], v[224:225], off offset:288
	s_waitcnt lgkmcnt(0)
	v_add_f32_e32 v214, v214, v216
	ds_bpermute_b32 v216, v211, v214
	s_and_saveexec_b64 s[52:53], s[4:5]
	s_waitcnt lgkmcnt(0)
	v_add_f32_e32 v214, v214, v216
	global_atomic_add_f32 v[204:205], v214, off offset:704
	s_or_b64 exec, exec, s[52:53]

.LBB0_574:
	s_or_b64 exec, exec, s[52:53]
	s_add_u32 s48, s74, s43
	s_addc_u32 s49, s75, s41
	s_waitcnt lgkmcnt(0)
	v_lshlrev_b64 v[224:225], 2, v[156:157]
	v_lshl_add_u64 v[226:227], s[48:49], 0, v[224:225]
	s_add_u32 s48, s76, s43
	s_addc_u32 s49, s77, s41
	v_lshl_add_u64 v[228:229], s[50:51], 0, v[224:225]
	v_lshl_add_u64 v[230:231], s[48:49], 0, v[224:225]
	global_load_dword v216, v[204:205], off offset:0 sc1
	global_load_dword v217, v[204:205], off offset:64 sc1
	global_load_dword v218, v[204:205], off offset:128 sc1
	global_load_dword v219, v[204:205], off offset:192 sc1
	global_load_dword v220, v[204:205], off offset:512 sc1
	global_load_dword v221, v[204:205], off offset:576 sc1
	global_load_dword v222, v[204:205], off offset:640 sc1
	global_load_dword v223, v[204:205], off offset:704 sc1
	global_load_dwordx4 v[160:163], v[226:227], off offset:0
	global_load_dwordx4 v[164:167], v[226:227], off offset:64
	global_load_dwordx4 v[168:171], v[226:227], off offset:512
	global_load_dwordx4 v[172:175], v[226:227], off offset:576
	global_load_dwordx4 v[176:179], v[228:229], off offset:0
	global_load_dwordx4 v[180:183], v[228:229], off offset:64
	global_load_dwordx4 v[184:187], v[228:229], off offset:512
	global_load_dwordx4 v[0:3], v[228:229], off offset:576
	global_load_dwordx4 v[116:119], v[230:231], off offset:0
	global_load_dwordx4 v[112:115], v[230:231], off offset:64
	global_load_dwordx4 v[108:111], v[230:231], off offset:512
	global_load_dwordx4 v[100:103], v[230:231], off offset:576
	v_lshlrev_b64 v[224:225], 1, v[156:157]
	v_lshlrev_b64 v[232:233], 11, v[158:159]
	v_lshl_add_u64 v[232:233], s[28:29], 0, v[232:233]
	v_lshl_add_u64 v[232:233], v[232:233], 0, v[224:225]
	s_andn2_b64 vcc, exec, s[8:9]
	s_mov_b64 s[8:9], -1
	s_mov_b32 s101, 0
	s_waitcnt vmcnt(4)
	v_pk_add_f32 v[160:161], v[160:161], 1.0 op_sel_hi:[1,0]
	v_pk_add_f32 v[162:163], v[162:163], 1.0 op_sel_hi:[1,0]
	v_pk_add_f32 v[164:165], v[164:165], 1.0 op_sel_hi:[1,0]
	v_pk_add_f32 v[166:167], v[166:167], 1.0 op_sel_hi:[1,0]
	v_pk_add_f32 v[168:169], v[168:169], 1.0 op_sel_hi:[1,0]
	v_pk_add_f32 v[170:171], v[170:171], 1.0 op_sel_hi:[1,0]
	v_pk_add_f32 v[172:173], v[172:173], 1.0 op_sel_hi:[1,0]
	v_pk_add_f32 v[174:175], v[174:175], 1.0 op_sel_hi:[1,0]
	v_pk_mul_f32 v[160:161], v[176:177], v[160:161]
	v_pk_mul_f32 v[162:163], v[178:179], v[162:163]
	v_pk_mul_f32 v[164:165], v[180:181], v[164:165]
	v_pk_mul_f32 v[166:167], v[182:183], v[166:167]
	v_pk_mul_f32 v[168:169], v[184:185], v[168:169]
	v_pk_mul_f32 v[170:171], v[186:187], v[170:171]
	v_pk_mul_f32 v[172:173], v[0:1], v[172:173]
	v_pk_mul_f32 v[174:175], v[2:3], v[174:175]
	s_waitcnt vmcnt(0)
	v_fmamk_f32 v194, v216, 0x3a800000, v202
	v_rsq_f32_e32 v194, v194
	s_nop 0
	v_pk_mul_f32 v[140:141], v[140:141], v[194:195] op_sel_hi:[1,0]
	v_pk_mul_f32 v[142:143], v[142:143], v[194:195] op_sel_hi:[1,0]
	v_pk_mul_f32 v[136:137], v[136:137], v[194:195] op_sel_hi:[1,0]
	v_pk_mul_f32 v[138:139], v[138:139], v[194:195] op_sel_hi:[1,0]
	v_pk_mul_f32 v[132:133], v[132:133], v[194:195] op_sel_hi:[1,0]
	v_pk_mul_f32 v[134:135], v[134:135], v[194:195] op_sel_hi:[1,0]
	v_pk_mul_f32 v[128:129], v[128:129], v[194:195] op_sel_hi:[1,0]
	v_pk_mul_f32 v[130:131], v[130:131], v[194:195] op_sel_hi:[1,0]
	v_pk_fma_f32 v[140:141], v[160:161], v[140:141], v[116:117]
	v_pk_fma_f32 v[142:143], v[162:163], v[142:143], v[118:119]
	v_pk_fma_f32 v[136:137], v[164:165], v[136:137], v[112:113]
	v_pk_fma_f32 v[138:139], v[166:167], v[138:139], v[114:115]
	v_pk_fma_f32 v[132:133], v[168:169], v[132:133], v[108:109]
	v_pk_fma_f32 v[134:135], v[170:171], v[134:135], v[110:111]
	v_pk_fma_f32 v[128:129], v[172:173], v[128:129], v[100:101]
	v_pk_fma_f32 v[130:131], v[174:175], v[130:131], v[102:103]
	v_cvt_pk_bf16_f32 v140, v140, v141
	v_cvt_pk_bf16_f32 v141, v142, v143
	global_store_dwordx2 v[232:233], v[140:141], off offset:0
	v_cvt_pk_bf16_f32 v136, v136, v137
	v_cvt_pk_bf16_f32 v137, v138, v139
	global_store_dwordx2 v[232:233], v[136:137], off offset:32
	v_cvt_pk_bf16_f32 v132, v132, v133
	v_cvt_pk_bf16_f32 v133, v134, v135
	global_store_dwordx2 v[232:233], v[132:133], off offset:256
	v_cvt_pk_bf16_f32 v128, v128, v129
	v_cvt_pk_bf16_f32 v129, v130, v131
	global_store_dwordx2 v[232:233], v[128:129], off offset:288
	v_fmamk_f32 v194, v217, 0x3a800000, v202
	v_rsq_f32_e32 v194, v194
	s_mov_b32 s100, 0x8000
	v_lshl_add_u64 v[192:193], v[232:233], 0, s[100:101]
	v_pk_mul_f32 v[124:125], v[124:125], v[194:195] op_sel_hi:[1,0]
	v_pk_mul_f32 v[126:127], v[126:127], v[194:195] op_sel_hi:[1,0]
	v_pk_mul_f32 v[120:121], v[120:121], v[194:195] op_sel_hi:[1,0]
	v_pk_mul_f32 v[122:123], v[122:123], v[194:195] op_sel_hi:[1,0]
	v_pk_mul_f32 v[104:105], v[104:105], v[194:195] op_sel_hi:[1,0]
	v_pk_mul_f32 v[106:107], v[106:107], v[194:195] op_sel_hi:[1,0]
	v_pk_mul_f32 v[96:97], v[96:97], v[194:195] op_sel_hi:[1,0]
	v_pk_mul_f32 v[98:99], v[98:99], v[194:195] op_sel_hi:[1,0]
	v_pk_fma_f32 v[124:125], v[160:161], v[124:125], v[116:117]
	v_pk_fma_f32 v[126:127], v[162:163], v[126:127], v[118:119]
	v_pk_fma_f32 v[120:121], v[164:165], v[120:121], v[112:113]
	v_pk_fma_f32 v[122:123], v[166:167], v[122:123], v[114:115]
	v_pk_fma_f32 v[104:105], v[168:169], v[104:105], v[108:109]
	v_pk_fma_f32 v[106:107], v[170:171], v[106:107], v[110:111]
	v_pk_fma_f32 v[96:97], v[172:173], v[96:97], v[100:101]
	v_pk_fma_f32 v[98:99], v[174:175], v[98:99], v[102:103]
	v_cvt_pk_bf16_f32 v124, v124, v125
	v_cvt_pk_bf16_f32 v125, v126, v127
	global_store_dwordx2 v[192:193], v[124:125], off offset:0
	v_cvt_pk_bf16_f32 v120, v120, v121
	v_cvt_pk_bf16_f32 v121, v122, v123
	global_store_dwordx2 v[192:193], v[120:121], off offset:32
	v_cvt_pk_bf16_f32 v104, v104, v105
	v_cvt_pk_bf16_f32 v105, v106, v107
	global_store_dwordx2 v[192:193], v[104:105], off offset:256
	v_cvt_pk_bf16_f32 v96, v96, v97
	v_cvt_pk_bf16_f32 v97, v98, v99
	global_store_dwordx2 v[192:193], v[96:97], off offset:288
	v_fmamk_f32 v194, v218, 0x3a800000, v202
	v_rsq_f32_e32 v194, v194
	s_mov_b32 s100, 0x10000
	v_lshl_add_u64 v[192:193], v[232:233], 0, s[100:101]
	v_pk_mul_f32 v[92:93], v[92:93], v[194:195] op_sel_hi:[1,0]
	v_pk_mul_f32 v[94:95], v[94:95], v[194:195] op_sel_hi:[1,0]
	v_pk_mul_f32 v[88:89], v[88:89], v[194:195] op_sel_hi:[1,0]
	v_pk_mul_f32 v[90:91], v[90:91], v[194:195] op_sel_hi:[1,0]
	v_pk_mul_f32 v[84:85], v[84:85], v[194:195] op_sel_hi:[1,0]
	v_pk_mul_f32 v[86:87], v[86:87], v[194:195] op_sel_hi:[1,0]
	v_pk_mul_f32 v[80:81], v[80:81], v[194:195] op_sel_hi:[1,0]
	v_pk_mul_f32 v[82:83], v[82:83], v[194:195] op_sel_hi:[1,0]
	v_pk_fma_f32 v[92:93], v[160:161], v[92:93], v[116:117]
	v_pk_fma_f32 v[94:95], v[162:163], v[94:95], v[118:119]
	v_pk_fma_f32 v[88:89], v[164:165], v[88:89], v[112:113]
	v_pk_fma_f32 v[90:91], v[166:167], v[90:91], v[114:115]
	v_pk_fma_f32 v[84:85], v[168:169], v[84:85], v[108:109]
	v_pk_fma_f32 v[86:87], v[170:171], v[86:87], v[110:111]
	v_pk_fma_f32 v[80:81], v[172:173], v[80:81], v[100:101]
	v_pk_fma_f32 v[82:83], v[174:175], v[82:83], v[102:103]
	v_cvt_pk_bf16_f32 v92, v92, v93
	v_cvt_pk_bf16_f32 v93, v94, v95
	global_store_dwordx2 v[192:193], v[92:93], off offset:0
	v_cvt_pk_bf16_f32 v88, v88, v89
	v_cvt_pk_bf16_f32 v89, v90, v91
	global_store_dwordx2 v[192:193], v[88:89], off offset:32
	v_cvt_pk_bf16_f32 v84, v84, v85
	v_cvt_pk_bf16_f32 v85, v86, v87
	global_store_dwordx2 v[192:193], v[84:85], off offset:256
	v_cvt_pk_bf16_f32 v80, v80, v81
	v_cvt_pk_bf16_f32 v81, v82, v83
	global_store_dwordx2 v[192:193], v[80:81], off offset:288
	v_fmamk_f32 v194, v219, 0x3a800000, v202
	v_rsq_f32_e32 v194, v194
	s_mov_b32 s100, 0x18000
	v_lshl_add_u64 v[192:193], v[232:233], 0, s[100:101]
	v_pk_mul_f32 v[76:77], v[76:77], v[194:195] op_sel_hi:[1,0]
	v_pk_mul_f32 v[78:79], v[78:79], v[194:195] op_sel_hi:[1,0]
	v_pk_mul_f32 v[72:73], v[72:73], v[194:195] op_sel_hi:[1,0]
	v_pk_mul_f32 v[74:75], v[74:75], v[194:195] op_sel_hi:[1,0]
	v_pk_mul_f32 v[68:69], v[68:69], v[194:195] op_sel_hi:[1,0]
	v_pk_mul_f32 v[70:71], v[70:71], v[194:195] op_sel_hi:[1,0]
	v_pk_mul_f32 v[64:65], v[64:65], v[194:195] op_sel_hi:[1,0]
	v_pk_mul_f32 v[66:67], v[66:67], v[194:195] op_sel_hi:[1,0]
	v_pk_fma_f32 v[76:77], v[160:161], v[76:77], v[116:117]
	v_pk_fma_f32 v[78:79], v[162:163], v[78:79], v[118:119]
	v_pk_fma_f32 v[72:73], v[164:165], v[72:73], v[112:113]
	v_pk_fma_f32 v[74:75], v[166:167], v[74:75], v[114:115]
	v_pk_fma_f32 v[68:69], v[168:169], v[68:69], v[108:109]
	v_pk_fma_f32 v[70:71], v[170:171], v[70:71], v[110:111]
	v_pk_fma_f32 v[64:65], v[172:173], v[64:65], v[100:101]
	v_pk_fma_f32 v[66:67], v[174:175], v[66:67], v[102:103]
	v_cvt_pk_bf16_f32 v76, v76, v77
	v_cvt_pk_bf16_f32 v77, v78, v79
	global_store_dwordx2 v[192:193], v[76:77], off offset:0
	v_cvt_pk_bf16_f32 v72, v72, v73
	v_cvt_pk_bf16_f32 v73, v74, v75
	global_store_dwordx2 v[192:193], v[72:73], off offset:32
	v_cvt_pk_bf16_f32 v68, v68, v69
	v_cvt_pk_bf16_f32 v69, v70, v71
	global_store_dwordx2 v[192:193], v[68:69], off offset:256
	v_cvt_pk_bf16_f32 v64, v64, v65
	v_cvt_pk_bf16_f32 v65, v66, v67
	global_store_dwordx2 v[192:193], v[64:65], off offset:288
	v_fmamk_f32 v194, v220, 0x3a800000, v202
	v_rsq_f32_e32 v194, v194
	s_mov_b32 s100, 0x40000
	v_lshl_add_u64 v[192:193], v[232:233], 0, s[100:101]
	v_pk_mul_f32 v[60:61], v[60:61], v[194:195] op_sel_hi:[1,0]
	v_pk_mul_f32 v[62:63], v[62:63], v[194:195] op_sel_hi:[1,0]
	v_pk_mul_f32 v[56:57], v[56:57], v[194:195] op_sel_hi:[1,0]
	v_pk_mul_f32 v[58:59], v[58:59], v[194:195] op_sel_hi:[1,0]
	v_pk_mul_f32 v[52:53], v[52:53], v[194:195] op_sel_hi:[1,0]
	v_pk_mul_f32 v[54:55], v[54:55], v[194:195] op_sel_hi:[1,0]
	v_pk_mul_f32 v[48:49], v[48:49], v[194:195] op_sel_hi:[1,0]
	v_pk_mul_f32 v[50:51], v[50:51], v[194:195] op_sel_hi:[1,0]
	v_pk_fma_f32 v[60:61], v[160:161], v[60:61], v[116:117]
	v_pk_fma_f32 v[62:63], v[162:163], v[62:63], v[118:119]
	v_pk_fma_f32 v[56:57], v[164:165], v[56:57], v[112:113]
	v_pk_fma_f32 v[58:59], v[166:167], v[58:59], v[114:115]
	v_pk_fma_f32 v[52:53], v[168:169], v[52:53], v[108:109]
	v_pk_fma_f32 v[54:55], v[170:171], v[54:55], v[110:111]
	v_pk_fma_f32 v[48:49], v[172:173], v[48:49], v[100:101]
	v_pk_fma_f32 v[50:51], v[174:175], v[50:51], v[102:103]
	v_cvt_pk_bf16_f32 v60, v60, v61
	v_cvt_pk_bf16_f32 v61, v62, v63
	global_store_dwordx2 v[192:193], v[60:61], off offset:0
	v_cvt_pk_bf16_f32 v56, v56, v57
	v_cvt_pk_bf16_f32 v57, v58, v59
	global_store_dwordx2 v[192:193], v[56:57], off offset:32
	v_cvt_pk_bf16_f32 v52, v52, v53
	v_cvt_pk_bf16_f32 v53, v54, v55
	global_store_dwordx2 v[192:193], v[52:53], off offset:256
	v_cvt_pk_bf16_f32 v48, v48, v49
	v_cvt_pk_bf16_f32 v49, v50, v51
	global_store_dwordx2 v[192:193], v[48:49], off offset:288
	v_fmamk_f32 v194, v221, 0x3a800000, v202
	v_rsq_f32_e32 v194, v194
	s_mov_b32 s100, 0x48000
	v_lshl_add_u64 v[192:193], v[232:233], 0, s[100:101]
	v_pk_mul_f32 v[44:45], v[44:45], v[194:195] op_sel_hi:[1,0]
	v_pk_mul_f32 v[46:47], v[46:47], v[194:195] op_sel_hi:[1,0]
	v_pk_mul_f32 v[40:41], v[40:41], v[194:195] op_sel_hi:[1,0]
	v_pk_mul_f32 v[42:43], v[42:43], v[194:195] op_sel_hi:[1,0]
	v_pk_mul_f32 v[36:37], v[36:37], v[194:195] op_sel_hi:[1,0]
	v_pk_mul_f32 v[38:39], v[38:39], v[194:195] op_sel_hi:[1,0]
	v_pk_mul_f32 v[32:33], v[32:33], v[194:195] op_sel_hi:[1,0]
	v_pk_mul_f32 v[34:35], v[34:35], v[194:195] op_sel_hi:[1,0]
	v_pk_fma_f32 v[44:45], v[160:161], v[44:45], v[116:117]
	v_pk_fma_f32 v[46:47], v[162:163], v[46:47], v[118:119]
	v_pk_fma_f32 v[40:41], v[164:165], v[40:41], v[112:113]
	v_pk_fma_f32 v[42:43], v[166:167], v[42:43], v[114:115]
	v_pk_fma_f32 v[36:37], v[168:169], v[36:37], v[108:109]
	v_pk_fma_f32 v[38:39], v[170:171], v[38:39], v[110:111]
	v_pk_fma_f32 v[32:33], v[172:173], v[32:33], v[100:101]
	v_pk_fma_f32 v[34:35], v[174:175], v[34:35], v[102:103]
	v_cvt_pk_bf16_f32 v44, v44, v45
	v_cvt_pk_bf16_f32 v45, v46, v47
	global_store_dwordx2 v[192:193], v[44:45], off offset:0
	v_cvt_pk_bf16_f32 v40, v40, v41
	v_cvt_pk_bf16_f32 v41, v42, v43
	global_store_dwordx2 v[192:193], v[40:41], off offset:32
	v_cvt_pk_bf16_f32 v36, v36, v37
	v_cvt_pk_bf16_f32 v37, v38, v39
	global_store_dwordx2 v[192:193], v[36:37], off offset:256
	v_cvt_pk_bf16_f32 v32, v32, v33
	v_cvt_pk_bf16_f32 v33, v34, v35
	global_store_dwordx2 v[192:193], v[32:33], off offset:288
	v_fmamk_f32 v194, v222, 0x3a800000, v202
	v_rsq_f32_e32 v194, v194
	s_mov_b32 s100, 0x50000
	v_lshl_add_u64 v[192:193], v[232:233], 0, s[100:101]
	v_pk_mul_f32 v[28:29], v[28:29], v[194:195] op_sel_hi:[1,0]
	v_pk_mul_f32 v[30:31], v[30:31], v[194:195] op_sel_hi:[1,0]
	v_pk_mul_f32 v[24:25], v[24:25], v[194:195] op_sel_hi:[1,0]
	v_pk_mul_f32 v[26:27], v[26:27], v[194:195] op_sel_hi:[1,0]
	v_pk_mul_f32 v[20:21], v[20:21], v[194:195] op_sel_hi:[1,0]
	v_pk_mul_f32 v[22:23], v[22:23], v[194:195] op_sel_hi:[1,0]
	v_pk_mul_f32 v[16:17], v[16:17], v[194:195] op_sel_hi:[1,0]
	v_pk_mul_f32 v[18:19], v[18:19], v[194:195] op_sel_hi:[1,0]
	v_pk_fma_f32 v[28:29], v[160:161], v[28:29], v[116:117]
	v_pk_fma_f32 v[30:31], v[162:163], v[30:31], v[118:119]
	v_pk_fma_f32 v[24:25], v[164:165], v[24:25], v[112:113]
	v_pk_fma_f32 v[26:27], v[166:167], v[26:27], v[114:115]
	v_pk_fma_f32 v[20:21], v[168:169], v[20:21], v[108:109]
	v_pk_fma_f32 v[22:23], v[170:171], v[22:23], v[110:111]
	v_pk_fma_f32 v[16:17], v[172:173], v[16:17], v[100:101]
	v_pk_fma_f32 v[18:19], v[174:175], v[18:19], v[102:103]
	v_cvt_pk_bf16_f32 v28, v28, v29
	v_cvt_pk_bf16_f32 v29, v30, v31
	global_store_dwordx2 v[192:193], v[28:29], off offset:0
	v_cvt_pk_bf16_f32 v24, v24, v25
	v_cvt_pk_bf16_f32 v25, v26, v27
	global_store_dwordx2 v[192:193], v[24:25], off offset:32
	v_cvt_pk_bf16_f32 v20, v20, v21
	v_cvt_pk_bf16_f32 v21, v22, v23
	global_store_dwordx2 v[192:193], v[20:21], off offset:256
	v_cvt_pk_bf16_f32 v16, v16, v17
	v_cvt_pk_bf16_f32 v17, v18, v19
	global_store_dwordx2 v[192:193], v[16:17], off offset:288
	v_fmamk_f32 v194, v223, 0x3a800000, v202
	v_rsq_f32_e32 v194, v194
	s_mov_b32 s100, 0x58000
	v_lshl_add_u64 v[192:193], v[232:233], 0, s[100:101]
	v_pk_mul_f32 v[12:13], v[12:13], v[194:195] op_sel_hi:[1,0]
	v_pk_mul_f32 v[14:15], v[14:15], v[194:195] op_sel_hi:[1,0]
	v_pk_mul_f32 v[8:9], v[8:9], v[194:195] op_sel_hi:[1,0]
	v_pk_mul_f32 v[10:11], v[10:11], v[194:195] op_sel_hi:[1,0]
	v_pk_mul_f32 v[4:5], v[4:5], v[194:195] op_sel_hi:[1,0]
	v_pk_mul_f32 v[6:7], v[6:7], v[194:195] op_sel_hi:[1,0]
	v_pk_mul_f32 v[188:189], v[188:189], v[194:195] op_sel_hi:[1,0]
	v_pk_mul_f32 v[190:191], v[190:191], v[194:195] op_sel_hi:[1,0]
	v_pk_fma_f32 v[12:13], v[160:161], v[12:13], v[116:117]
	v_pk_fma_f32 v[14:15], v[162:163], v[14:15], v[118:119]
	v_pk_fma_f32 v[8:9], v[164:165], v[8:9], v[112:113]
	v_pk_fma_f32 v[10:11], v[166:167], v[10:11], v[114:115]
	v_pk_fma_f32 v[4:5], v[168:169], v[4:5], v[108:109]
	v_pk_fma_f32 v[6:7], v[170:171], v[6:7], v[110:111]
	v_pk_fma_f32 v[188:189], v[172:173], v[188:189], v[100:101]
	v_pk_fma_f32 v[190:191], v[174:175], v[190:191], v[102:103]
	v_cvt_pk_bf16_f32 v12, v12, v13
	v_cvt_pk_bf16_f32 v13, v14, v15
	global_store_dwordx2 v[192:193], v[12:13], off offset:0
	v_cvt_pk_bf16_f32 v8, v8, v9
	v_cvt_pk_bf16_f32 v9, v10, v11
	global_store_dwordx2 v[192:193], v[8:9], off offset:32
	v_cvt_pk_bf16_f32 v4, v4, v5
	v_cvt_pk_bf16_f32 v5, v6, v7
	global_store_dwordx2 v[192:193], v[4:5], off offset:256
	v_cvt_pk_bf16_f32 v188, v188, v189
	v_cvt_pk_bf16_f32 v189, v190, v191
	global_store_dwordx2 v[192:193], v[188:189], off offset:288
	s_cbranch_vccnz .LBB0_536
	s_andn2_b64 vcc, exec, s[0:1]
	s_cbranch_vccnz .LBB0_535
	s_barrier
	s_branch .LBB0_535
